# attention tile staging: LDS write addresses via immediate offsets (8 fewer VALU per tile)
# baseline (speedup 1.0000x reference)
; #define SWRITE(B) do { _Pragma("unroll") for (int ii = 0; ii < 4; ++ii) { const int row = sr + 16 * ii; \
;       *(u32x4*)(K_lds0 + (B) * 32768 + KSWZ(row, sc * 2)) = stk[ii]; *(u32x4*)(V_lds0 + (B) * 32768 + v_st(row, sc)) = stv[ii]; } } while (0)
; __device__ __forceinline__ void attn_phase(const Params& p, char* smem, int bid, int nblk) {
;     ...
;       if (kt > 0) SWRITE(cur ^ 1);
.LBB0_1802:
	s_or_b64 exec, exec, s[44:45]
	s_andn2_b64 vcc, exec, s[42:43]
	s_cbranch_vccnz .LBB0_1787
	s_xor_b32 s0, s56, 0x8000
	v_add_u32_e32 v64, s0, v222
	v_add_u32_e32 v65, s0, v223
	s_waitcnt vmcnt(7)
	ds_write_b128 v64, v[112:115]
	s_waitcnt vmcnt(6)
	ds_write_b128 v65, v[116:119] offset:16384
	s_waitcnt vmcnt(5)
	ds_write_b128 v64, v[120:123] offset:4096
	s_waitcnt vmcnt(4)
	ds_write_b128 v65, v[124:127] offset:20480
	s_waitcnt vmcnt(3)
	ds_write_b128 v64, v[128:131] offset:8192
	s_waitcnt vmcnt(2)
	ds_write_b128 v65, v[132:135] offset:24576
	s_waitcnt vmcnt(1)
	ds_write_b128 v64, v[136:139] offset:12288
	s_waitcnt vmcnt(0)
	ds_write_b128 v65, v[140:143] offset:28672
	s_branch .LBB0_1787
